# P0 rms row stores widened dwordx2->dwordx4 via DPP lane-pair exchange
# speedup vs baseline: 1.0048x; 1.0048x over previous
; __device__ __forceinline__ unsigned pk2(float lo, float hi) { f32x2_t v = {lo, hi}; bf16x2_t b = __builtin_convertvector(v, bf16x2_t); return __builtin_bit_cast(unsigned, b); }
; __device__ __forceinline__ void rms_row2048(const float* xrow, const float* g, bf16_t* orow, int lane) {
;     const f32x4* xr = (const f32x4*)xrow + lane; const f32x4* gr = (const f32x4*)g + lane;
;     f32x4 v[8]; float s = 0.f;
; #pragma unroll
;     for (int j = 0; j < 8; ++j) { v[j] = xr[64 * j]; s += (v[j].x * v[j].x + v[j].y * v[j].y) + (v[j].z * v[j].z + v[j].w * v[j].w); }
;     const float r = rsqrtf(wave_sum(s) * (1.f / 2048.f) + EPS);
;     u32x2* o8 = (u32x2*)orow + lane;
; #pragma unroll
;     for (int j = 0; j < 8; ++j) { const f32x4 gg = gr[64 * j]; u32x2 w; w.x = pk2(v[j].x * r * gg.x, v[j].y * r * gg.y); w.y = pk2(v[j].z * r * gg.z, v[j].w * r * gg.w); o8[64 * j] = w; }
; __global__ void __launch_bounds__(512, 2) mega_fwd(Args args) {
;     ...
;         for (int m = gw; m < T; m += NGW) rms_row2048(x + (size_t)m * D, args.in[3], H + (size_t)m * D, lane);
.LBB0_257:
	s_or_b64 exec, exec, s[2:3]
	v_readlane_b32 s0, v238, 38
	s_cmpk_gt_i32 s0, 0x3fff
	v_readlane_b32 s1, v238, 39
	s_cbranch_scc1 .LBB0_260
	v_lshlrev_b32_e32 v0, 4, v184
	v_mov_b32_e32 v1, 0
	v_lshl_add_u64 v[16:17], s[58:59], 0, v[0:1]
	s_mov_b64 s[0:1], 0x1000
	v_lshl_add_u64 v[18:19], v[16:17], 0, s[0:1]
	s_mov_b64 s[0:1], 0x1400
	v_lshl_add_u64 v[20:21], v[16:17], 0, s[0:1]
	s_mov_b64 s[0:1], 0x1800
	v_lshl_add_u64 v[22:23], v[16:17], 0, s[0:1]
	v_readlane_b32 s0, v238, 38
	v_readlane_b32 s1, v238, 39
	s_mov_b32 s8, s0
	s_ashr_i32 s9, s0, 31
	s_lshl_b64 s[0:1], s[8:9], 12
	s_add_u32 s0, s86, s0
	v_lshlrev_b32_e32 v2, 3, v184
	v_mov_b32_e32 v3, v1
	s_addc_u32 s1, s87, s1
	v_lshl_add_u64 v[2:3], s[0:1], 0, v[2:3]
	s_mov_b64 s[0:1], 0x6800e00
	s_ashr_i32 s97, s96, 31
	v_lshl_add_u64 v[26:27], v[2:3], 0, s[0:1]
	s_lshl_b64 s[0:1], s[96:97], 12
	s_lshl_b64 s[4:5], s[8:9], 13
	s_add_u32 s4, s52, s4
	s_addc_u32 s5, s53, s5
	s_mov_b64 s[2:3], 0x1c00
	v_lshl_add_u64 v[0:1], s[4:5], 0, v[0:1]
	s_mov_b32 s6, s8
	v_lshl_add_u64 v[24:25], v[16:17], 0, s[2:3]
	v_lshl_add_u64 v[28:29], v[0:1], 0, s[2:3]
	s_lshl_b64 s[2:3], s[96:97], 13
	v_mov_b32_e32 v30, 0x358637bd
	s_mov_b32 s4, 0x800000
	v_writelane_b32 v238, s6, 38
	s_mov_b32 s5, s8
	s_nop 0
	v_writelane_b32 v238, s7, 39
	global_load_dwordx4 v[80:83], v[16:17], off nt
	global_load_dwordx4 v[84:87], v[16:17], off offset:1024 nt
	global_load_dwordx4 v[88:91], v[16:17], off offset:2048 nt
	global_load_dwordx4 v[92:95], v[16:17], off offset:3072 nt
	global_load_dwordx4 v[96:99], v[18:19], off nt
	global_load_dwordx4 v[100:103], v[20:21], off nt
	global_load_dwordx4 v[104:107], v[22:23], off nt
	global_load_dwordx4 v[108:111], v[24:25], off nt
	v_add_co_u32_e32 v144, vcc, 0xfffff000, v28
	global_load_dwordx4 v[112:115], v[28:29], off offset:-3072 nt
	global_load_dwordx4 v[116:119], v[28:29], off offset:-2048 nt
	global_load_dwordx4 v[120:123], v[28:29], off offset:-1024 nt
	v_addc_co_u32_e32 v145, vcc, -1, v29, vcc
	global_load_dwordx4 v[124:127], v[144:145], off offset:-3072 nt
	global_load_dwordx4 v[128:131], v[144:145], off offset:-2048 nt
	global_load_dwordx4 v[132:135], v[144:145], off offset:-1024 nt
	global_load_dwordx4 v[136:139], v[28:29], off offset:-4096 nt
	s_nop 0
	global_load_dwordx4 v[140:143], v[28:29], off nt
	s_add_i32 s5, s5, s96
	s_cmpk_lt_i32 s5, 0x4000
	v_lshl_add_u64 v[28:29], v[28:29], 0, s[2:3]
	s_cselect_b32 s16, 1, 0
	s_waitcnt vmcnt(0)
	v_and_b32_e32 v244, 1, v184
	v_lshrrev_b32_e32 v245, 1, v184
	v_lshlrev_b32_e32 v244, 9, v244
	v_lshl_add_u32 v244, v245, 4, v244
	v_lshlrev_b32_e32 v245, 3, v184
	v_sub_u32_e32 v244, v244, v245
	v_ashrrev_i32_e32 v245, 31, v244
	v_lshl_add_u64 v[26:27], v[26:27], 0, v[244:245]
	s_mov_b32 s12, 0xaaaaaaaa
	s_mov_b32 s13, 0xaaaaaaaa

; __device__ __forceinline__ unsigned pk2(float lo, float hi) { f32x2_t v = {lo, hi}; bf16x2_t b = __builtin_convertvector(v, bf16x2_t); return __builtin_bit_cast(unsigned, b); }
; __device__ __forceinline__ void rms_row2048(const float* xrow, const float* g, bf16_t* orow, int lane) {
;     ...
;     f32x4 v[8]; float s = 0.f;
; #pragma unroll
;     for (int j = 0; j < 8; ++j) { v[j] = xr[64 * j]; s += (v[j].x * v[j].x + v[j].y * v[j].y) + (v[j].z * v[j].z + v[j].w * v[j].w); }
;     const float r = rsqrtf(wave_sum(s) * (1.f / 2048.f) + EPS);
;     u32x2* o8 = (u32x2*)orow + lane;
; #pragma unroll
;     for (int j = 0; j < 8; ++j) { const f32x4 gg = gr[64 * j]; u32x2 w; w.x = pk2(v[j].x * r * gg.x, v[j].y * r * gg.y); w.y = pk2(v[j].z * r * gg.z, v[j].w * r * gg.w); o8[64 * j] = w; }
.Lp0r_nopref:
	v_mov_b32_e32 v68, v35
	v_pk_mul_f32 v[52:53], v[14:15], v[14:15]
	v_pk_mul_f32 v[54:55], v[12:13], v[12:13]
	v_mul_f32_e32 v56, v9, v9
	v_mul_f32_e32 v58, v11, v11
	v_mul_f32_e32 v64, v2, v2
	v_mul_f32_e32 v65, v3, v3
	v_pk_mov_b32 v[60:61], v[54:55], v[52:53] op_sel:[1,0]
	v_mov_b32_e32 v55, v53
	v_pk_fma_f32 v[52:53], v[8:9], v[8:9], v[56:57] op_sel_hi:[1,1,0]
	v_pk_fma_f32 v[56:57], v[10:11], v[10:11], v[58:59] op_sel_hi:[1,1,0]
	v_pk_mul_f32 v[62:63], v[42:43], v[42:43]
	v_pk_add_f32 v[54:55], v[60:61], v[54:55]
	v_pk_mul_f32 v[60:61], v[40:41], v[40:41]
	v_mov_b32_e32 v53, v64
	v_mov_b32_e32 v57, v65
	v_mov_b32_e32 v64, v33
	v_mov_b32_e32 v65, v37
	v_mov_b32_e32 v69, v39
	v_mov_b32_e32 v58, v32
	v_mov_b32_e32 v59, v36
	v_mov_b32_e32 v66, v34
	v_mov_b32_e32 v67, v38
	v_pk_mov_b32 v[74:75], v[60:61], v[62:63] op_sel:[1,0]
	v_mov_b32_e32 v61, v63
	v_pk_add_f32 v[52:53], v[52:53], v[56:57]
	v_pk_mul_f32 v[56:57], v[64:65], v[64:65]
	v_pk_mul_f32 v[62:63], v[68:69], v[68:69]
	v_pk_fma_f32 v[56:57], v[58:59], v[58:59], v[56:57]
	v_pk_fma_f32 v[58:59], v[66:67], v[66:67], v[62:63]
	v_mul_f32_e32 v71, v5, v5
	v_mul_f32_e32 v73, v6, v6
	v_mul_f32_e32 v70, v45, v45
	v_mul_f32_e32 v72, v47, v47
	v_pk_add_f32 v[60:61], v[74:75], v[60:61]
	v_pk_add_f32 v[56:57], v[56:57], v[58:59]
	v_mul_f32_e32 v31, v4, v4
	v_mul_f32_e32 v76, v7, v7
	v_pk_fma_f32 v[64:65], v[44:45], v[44:45], v[70:71] op_sel_hi:[1,1,0]
	v_pk_fma_f32 v[68:69], v[46:47], v[46:47], v[72:73] op_sel_hi:[1,1,0]
	v_pk_add_f32 v[58:59], v[60:61], v[60:61] op_sel:[0,1] op_sel_hi:[1,0]
	v_pk_add_f32 v[56:57], v[56:57], v[56:57] op_sel:[0,1] op_sel_hi:[1,0]
	v_mov_b32_e32 v65, v73
	v_mov_b32_e32 v69, v76
	v_mov_b32_e32 v59, v71
	v_mov_b32_e32 v57, v31
	v_pk_add_f32 v[60:61], v[64:65], v[68:69]
	v_pk_add_f32 v[56:57], v[56:57], v[58:59]
	v_mul_f32_e32 v77, v1, v1
	v_pk_add_f32 v[56:57], v[56:57], v[60:61]
	v_mul_f32_e32 v78, v0, v0
	v_pk_add_f32 v[54:55], v[54:55], v[54:55] op_sel:[0,1] op_sel_hi:[1,0]
	v_pk_add_f32 v[56:57], v[56:57], v[56:57] op_sel:[0,1] op_sel_hi:[1,0]
	v_mov_b32_e32 v55, v77
	v_mov_b32_e32 v57, v78
	v_pk_add_f32 v[54:55], v[56:57], v[54:55]
	s_nop 0
	v_pk_add_f32 v[52:53], v[54:55], v[52:53]
	s_nop 0
	v_add_f32_e32 v31, v52, v53
	s_nop 1
	v_add_f32_dpp v31, v31, v31 quad_perm:[1,0,3,2] row_mask:0xf bank_mask:0xf bound_ctrl:1
	s_nop 1
	v_add_f32_dpp v31, v31, v31 quad_perm:[2,3,0,1] row_mask:0xf bank_mask:0xf bound_ctrl:1
	s_nop 1
	v_add_f32_dpp v31, v31, v31 row_half_mirror row_mask:0xf bank_mask:0xf bound_ctrl:1
	s_nop 1
	v_add_f32_dpp v31, v31, v31 row_mirror row_mask:0xf bank_mask:0xf bound_ctrl:1
	s_nop 0
	v_readlane_b32 s8, v31, 16
	v_readlane_b32 s9, v31, 48
	v_readlane_b32 s6, v31, 0
	v_readlane_b32 s7, v31, 32
	v_mov_b32_e32 v52, s8
	v_mov_b32_e32 v53, s9
	v_pk_add_f32 v[52:53], s[6:7], v[52:53]
	s_nop 0
	v_add_f32_e32 v31, v52, v53
	v_fmamk_f32 v31, v31, 0x3a000000, v30
	v_mul_f32_e32 v52, 0x4b800000, v31
	v_cmp_gt_f32_e32 vcc, s4, v31
	s_nop 1
	v_cndmask_b32_e32 v31, v31, v52, vcc
	v_rsq_f32_e32 v31, v31
	s_nop 0
	v_mul_f32_e32 v52, 0x45800000, v31
	v_cndmask_b32_e32 v52, v31, v52, vcc
	v_pk_mul_f32 v[32:33], v[32:33], v[52:53] op_sel_hi:[1,0]
	v_pk_mul_f32 v[34:35], v[34:35], v[52:53] op_sel_hi:[1,0]
	v_pk_mul_f32 v[36:37], v[36:37], v[52:53] op_sel_hi:[1,0]
	v_pk_mul_f32 v[38:39], v[38:39], v[52:53] op_sel_hi:[1,0]
	v_pk_mul_f32 v[40:41], v[40:41], v[52:53] op_sel_hi:[1,0]
	v_pk_mul_f32 v[42:43], v[42:43], v[52:53] op_sel_hi:[1,0]
	v_pk_mul_f32 v[44:45], v[44:45], v[52:53] op_sel_hi:[1,0]
	v_pk_mul_f32 v[46:47], v[46:47], v[52:53] op_sel_hi:[1,0]
	v_pk_mul_f32 v[4:5], v[4:5], v[52:53] op_sel_hi:[1,0]
	v_pk_mul_f32 v[6:7], v[6:7], v[52:53] op_sel_hi:[1,0]
; __device__ __forceinline__ unsigned pk2(float lo, float hi) { f32x2_t v = {lo, hi}; bf16x2_t b = __builtin_convertvector(v, bf16x2_t); return __builtin_bit_cast(unsigned, b); }
; __device__ __forceinline__ void rms_row2048(const float* xrow, const float* g, bf16_t* orow, int lane) {
;     ...
; #pragma unroll
;     for (int j = 0; j < 8; ++j) { const f32x4 gg = gr[64 * j]; u32x2 w; w.x = pk2(v[j].x * r * gg.x, v[j].y * r * gg.y); w.y = pk2(v[j].z * r * gg.z, v[j].w * r * gg.w); o8[64 * j] = w; }
; __global__ void __launch_bounds__(512, 2) mega_fwd(Args args) {
;     ...
;         for (int m = gw; m < T; m += NGW) rms_row2048(x + (size_t)m * D, args.in[3], H + (size_t)m * D, lane);
	v_pk_mul_f32 v[12:13], v[12:13], v[52:53] op_sel_hi:[1,0]
	v_pk_mul_f32 v[14:15], v[14:15], v[52:53] op_sel_hi:[1,0]
	v_pk_mul_f32 v[8:9], v[8:9], v[52:53] op_sel_hi:[1,0]
	v_pk_mul_f32 v[10:11], v[10:11], v[52:53] op_sel_hi:[1,0]
	v_pk_mul_f32 v[0:1], v[0:1], v[52:53] op_sel_hi:[1,0]
	v_pk_mul_f32 v[2:3], v[2:3], v[52:53] op_sel_hi:[1,0]
	v_pk_mul_f32 v[32:33], v[80:81], v[32:33]
	v_pk_mul_f32 v[34:35], v[82:83], v[34:35]
	v_pk_mul_f32 v[36:37], v[84:85], v[36:37]
	v_pk_mul_f32 v[38:39], v[86:87], v[38:39]
	v_pk_mul_f32 v[40:41], v[88:89], v[40:41]
	v_pk_mul_f32 v[42:43], v[90:91], v[42:43]
	v_pk_mul_f32 v[44:45], v[92:93], v[44:45]
	v_pk_mul_f32 v[46:47], v[94:95], v[46:47]
	v_pk_mul_f32 v[4:5], v[96:97], v[4:5]
	v_pk_mul_f32 v[6:7], v[98:99], v[6:7]
	v_pk_mul_f32 v[12:13], v[100:101], v[12:13]
	v_pk_mul_f32 v[14:15], v[102:103], v[14:15]
	v_pk_mul_f32 v[8:9], v[104:105], v[8:9]
	v_pk_mul_f32 v[10:11], v[106:107], v[10:11]
	v_pk_mul_f32 v[0:1], v[108:109], v[0:1]
	v_pk_mul_f32 v[2:3], v[110:111], v[2:3]
	v_cvt_pk_bf16_f32 v32, v32, v33
	v_cvt_pk_bf16_f32 v33, v34, v35
	v_cvt_pk_bf16_f32 v36, v36, v37
	v_cvt_pk_bf16_f32 v37, v38, v39
	v_cvt_pk_bf16_f32 v40, v40, v41
	v_cvt_pk_bf16_f32 v41, v42, v43
	v_cvt_pk_bf16_f32 v44, v44, v45
	v_cvt_pk_bf16_f32 v45, v46, v47
	v_cvt_pk_bf16_f32 v4, v4, v5
	v_cvt_pk_bf16_f32 v5, v6, v7
	v_cvt_pk_bf16_f32 v12, v12, v13
	v_cvt_pk_bf16_f32 v13, v14, v15
	v_cvt_pk_bf16_f32 v8, v8, v9
	v_cvt_pk_bf16_f32 v9, v10, v11
	v_cvt_pk_bf16_f32 v0, v0, v1
	v_cvt_pk_bf16_f32 v1, v2, v3
	v_mov_b32_dpp v244, v32 quad_perm:[1,0,3,2] row_mask:0xf bank_mask:0xf
	v_mov_b32_dpp v245, v33 quad_perm:[1,0,3,2] row_mask:0xf bank_mask:0xf
	v_mov_b32_dpp v246, v36 quad_perm:[1,0,3,2] row_mask:0xf bank_mask:0xf
	v_mov_b32_dpp v247, v37 quad_perm:[1,0,3,2] row_mask:0xf bank_mask:0xf
	v_cndmask_b32_e64 v240, v32, v246, s[12:13]
	v_cndmask_b32_e64 v241, v33, v247, s[12:13]
	v_cndmask_b32_e64 v242, v244, v36, s[12:13]
	v_cndmask_b32_e64 v243, v245, v37, s[12:13]
	global_store_dwordx4 v[26:27], v[240:243], off offset:-3584
	v_mov_b32_dpp v244, v40 quad_perm:[1,0,3,2] row_mask:0xf bank_mask:0xf
	v_mov_b32_dpp v245, v41 quad_perm:[1,0,3,2] row_mask:0xf bank_mask:0xf
	v_mov_b32_dpp v246, v44 quad_perm:[1,0,3,2] row_mask:0xf bank_mask:0xf
	v_mov_b32_dpp v247, v45 quad_perm:[1,0,3,2] row_mask:0xf bank_mask:0xf
	v_cndmask_b32_e64 v240, v40, v246, s[12:13]
	v_cndmask_b32_e64 v241, v41, v247, s[12:13]
	v_cndmask_b32_e64 v242, v244, v44, s[12:13]
	v_cndmask_b32_e64 v243, v245, v45, s[12:13]
	global_store_dwordx4 v[26:27], v[240:243], off offset:-2560
	v_mov_b32_dpp v244, v4 quad_perm:[1,0,3,2] row_mask:0xf bank_mask:0xf
	v_mov_b32_dpp v245, v5 quad_perm:[1,0,3,2] row_mask:0xf bank_mask:0xf
	v_mov_b32_dpp v246, v12 quad_perm:[1,0,3,2] row_mask:0xf bank_mask:0xf
	v_mov_b32_dpp v247, v13 quad_perm:[1,0,3,2] row_mask:0xf bank_mask:0xf
	v_cndmask_b32_e64 v240, v4, v246, s[12:13]
	v_cndmask_b32_e64 v241, v5, v247, s[12:13]
	v_cndmask_b32_e64 v242, v244, v12, s[12:13]
	v_cndmask_b32_e64 v243, v245, v13, s[12:13]
	global_store_dwordx4 v[26:27], v[240:243], off offset:-1536
	v_mov_b32_dpp v244, v8 quad_perm:[1,0,3,2] row_mask:0xf bank_mask:0xf
	v_mov_b32_dpp v245, v9 quad_perm:[1,0,3,2] row_mask:0xf bank_mask:0xf
	v_mov_b32_dpp v246, v0 quad_perm:[1,0,3,2] row_mask:0xf bank_mask:0xf
	v_mov_b32_dpp v247, v1 quad_perm:[1,0,3,2] row_mask:0xf bank_mask:0xf
	v_cndmask_b32_e64 v240, v8, v246, s[12:13]
	v_cndmask_b32_e64 v241, v9, v247, s[12:13]
	v_cndmask_b32_e64 v242, v244, v0, s[12:13]
	v_cndmask_b32_e64 v243, v245, v1, s[12:13]
	global_store_dwordx4 v[26:27], v[240:243], off offset:-512
	v_lshl_add_u64 v[26:27], v[26:27], 0, s[0:1]
	s_cmp_lg_u32 s17, 0
	s_cbranch_scc0 .Lp0r_done
	s_waitcnt vmcnt(4)
	s_branch .LBB0_259
